# static priority (guide 6.3): P5 K-loop: per-block s_setprio flips deleted, one static s_setprio 1 for waves 4..7 at K-loop entry, reset at exit
# speedup vs baseline: 1.0054x; 1.0054x over previous
; #define PG8_STAGE(bufoff, gbase, voff) do { _Pragma("unroll") for (int _i = 0; _i < 2; ++_i) \
;         __builtin_amdgcn_global_load_lds((const unsigned*)((const char*)(gbase) + (voff)[_i]), (PG8_LAS unsigned*)(lds + (bufoff) + ldsw + _i * 8192), 16, 0, 0); } while (0)
; #define PG8_LDA(dst, b, h) do { _Pragma("unroll") for (int m = 0; m < 4; ++m) _Pragma("unroll") for (int k = 0; k < 2; ++k) dst[m][k] = *(const PG8_LAS bf16x8*)(lds + PG8_SA(b, h) + aoff + m * 2048 + k * 1024); } while (0)
; #define PG8_LDB(dst, b, h) do { _Pragma("unroll") for (int n = 0; n < 2; ++n) _Pragma("unroll") for (int k = 0; k < 2; ++k) dst[n][k] = *(const PG8_LAS bf16x8*)(lds + PG8_SB(b, h) + boff + n * 2048 + k * 1024); } while (0)
; #define PG8_MMA(ai, bj, At, Bt) do { __builtin_amdgcn_s_setprio(1); _Pragma("unroll") for (int m = 0; m < 4; ++m) _Pragma("unroll") for (int n = 0; n < 2; ++n) _Pragma("unroll") for (int k = 0; k < 2; ++k) \
;         acc[ai][bj][m][n] = __builtin_amdgcn_mfma_f32_16x16x32_bf16(Bt[n][k], At[m][k], acc[ai][bj][m][n], 0, 0, 0); __builtin_amdgcn_s_setprio(0); } while (0)
; #define PG8_WAIT_V(n) asm volatile("s_waitcnt vmcnt(" #n ")" ::: "memory")
; #define PG8_WAIT_L(n) asm volatile("s_waitcnt lgkmcnt(" #n ")" ::: "memory")
; #define PG8_BAR __builtin_amdgcn_s_barrier()
; #define PG8_SCHED __builtin_amdgcn_sched_barrier(0)
; template <class Epi, class Sched, bool ALIGN_EPI = false, bool SP2 = false>
; __device__ __forceinline__ void gemm_phase(PG8_LAS unsigned char* lds, const Gemm g, const Sched& S, const Epi& E) {
;     ...
;             PG8_LDB(B0, 0, 0); PG8_LDB(B1, 0, 1); PG8_SCHED; PG8_LDA(At, 0, 0); PG8_STAGE(PG8_SA(1, 1), a1 + hstep, voffA);
;             PG8_WAIT_V(8); PG8_WAIT_L(0); PG8_BAR; PG8_MMA(0, 0, At, B0); PG8_MMA(0, 1, At, B1); PG8_BAR; PG8_SCHED;
;     ...
;         for (int a = 0; a < 2; ++a)
; #pragma unroll
;             for (int b = 0; b < 2; ++b)
; #pragma unroll
;                 for (int m = 0; m < 4; ++m)
; #pragma unroll
;                     for (int n = 0; n < 2; ++n) acc[a][b][m][n] = (f32x4){0.f, 0.f, 0.f, 0.f};
.LBB0_573:
	s_ashr_i32 s63, s62, 31
	s_lshl_b64 s[16:17], s[62:63], 19
	s_add_u32 s66, s59, s16
	s_addc_u32 s67, s73, s17
	s_and_b64 s[10:11], s[10:11], exec
	s_cselect_b32 s16, s67, s13
	s_cselect_b32 s17, s66, s12
	s_add_u32 s10, s14, 0x40080
	s_addc_u32 s11, s15, 0
	s_add_u32 s19, s12, 0x100
	v_mov_b32_e32 v96, 0
	s_addc_u32 s20, s13, 0
	s_mov_b32 s21, -2
	v_mov_b32_e32 v97, v96
	v_mov_b32_e32 v98, v96
	v_mov_b32_e32 v99, v96
	v_mov_b32_e32 v100, v96
	v_mov_b32_e32 v101, v96
	v_mov_b32_e32 v102, v96
	v_mov_b32_e32 v103, v96
	v_mov_b32_e32 v0, v96
	v_mov_b32_e32 v1, v96
	v_mov_b32_e32 v2, v96
	v_mov_b32_e32 v3, v96
	v_mov_b32_e32 v48, v96
	v_mov_b32_e32 v49, v96
	v_mov_b32_e32 v50, v96
	v_mov_b32_e32 v51, v96
	v_mov_b32_e32 v8, v96
	v_mov_b32_e32 v9, v96
	v_mov_b32_e32 v10, v96
	v_mov_b32_e32 v11, v96
	v_mov_b32_e32 v56, v96
	v_mov_b32_e32 v57, v96
	v_mov_b32_e32 v58, v96
	v_mov_b32_e32 v59, v96
	v_mov_b32_e32 v16, v96
	v_mov_b32_e32 v17, v96
	v_mov_b32_e32 v18, v96
	v_mov_b32_e32 v19, v96
	v_mov_b32_e32 v64, v96
	v_mov_b32_e32 v65, v96
	v_mov_b32_e32 v66, v96
	v_mov_b32_e32 v67, v96
	v_mov_b32_e32 v104, v96
	v_mov_b32_e32 v105, v96
	v_mov_b32_e32 v106, v96
	v_mov_b32_e32 v107, v96
	v_mov_b32_e32 v108, v96
	v_mov_b32_e32 v109, v96
	v_mov_b32_e32 v110, v96
	v_mov_b32_e32 v111, v96
	v_mov_b32_e32 v4, v96
	v_mov_b32_e32 v5, v96
	v_mov_b32_e32 v6, v96
	v_mov_b32_e32 v7, v96
	v_mov_b32_e32 v52, v96
	v_mov_b32_e32 v53, v96
	v_mov_b32_e32 v54, v96
	v_mov_b32_e32 v55, v96
	v_mov_b32_e32 v12, v96
	v_mov_b32_e32 v13, v96
	v_mov_b32_e32 v14, v96
	v_mov_b32_e32 v15, v96
	v_mov_b32_e32 v60, v96
	v_mov_b32_e32 v61, v96
	v_mov_b32_e32 v62, v96
	v_mov_b32_e32 v63, v96
	v_mov_b32_e32 v20, v96
	v_mov_b32_e32 v21, v96
	v_mov_b32_e32 v22, v96
	v_mov_b32_e32 v23, v96
	v_mov_b32_e32 v68, v96
	v_mov_b32_e32 v69, v96
	v_mov_b32_e32 v70, v96
	v_mov_b32_e32 v71, v96
	v_mov_b32_e32 v112, v96
	v_mov_b32_e32 v113, v96
	v_mov_b32_e32 v114, v96
	v_mov_b32_e32 v115, v96
	v_mov_b32_e32 v116, v96
	v_mov_b32_e32 v117, v96
	v_mov_b32_e32 v118, v96
	v_mov_b32_e32 v119, v96
	v_mov_b32_e32 v24, v96
	v_mov_b32_e32 v25, v96
	v_mov_b32_e32 v26, v96
	v_mov_b32_e32 v27, v96
	v_mov_b32_e32 v72, v96
	v_mov_b32_e32 v73, v96
	v_mov_b32_e32 v74, v96
	v_mov_b32_e32 v75, v96
	v_mov_b32_e32 v32, v96
	v_mov_b32_e32 v33, v96
	v_mov_b32_e32 v34, v96
	v_mov_b32_e32 v35, v96
	v_mov_b32_e32 v80, v96
	v_mov_b32_e32 v81, v96
	v_mov_b32_e32 v82, v96
	v_mov_b32_e32 v83, v96
	v_mov_b32_e32 v40, v96
	v_mov_b32_e32 v41, v96
	v_mov_b32_e32 v42, v96
	v_mov_b32_e32 v43, v96
	v_mov_b32_e32 v88, v96
	v_mov_b32_e32 v89, v96
	v_mov_b32_e32 v90, v96
	v_mov_b32_e32 v91, v96
	v_mov_b32_e32 v120, v96
	v_mov_b32_e32 v121, v96
	v_mov_b32_e32 v122, v96
	v_mov_b32_e32 v123, v96
	v_mov_b32_e32 v124, v96
	v_mov_b32_e32 v125, v96
	v_mov_b32_e32 v126, v96
	v_mov_b32_e32 v127, v96
	v_mov_b32_e32 v28, v96
	v_mov_b32_e32 v29, v96
	v_mov_b32_e32 v30, v96
	v_mov_b32_e32 v31, v96
	v_mov_b32_e32 v76, v96
	v_mov_b32_e32 v77, v96
	v_mov_b32_e32 v78, v96
	v_mov_b32_e32 v79, v96
	v_mov_b32_e32 v36, v96
	v_mov_b32_e32 v37, v96
	v_mov_b32_e32 v38, v96
	v_mov_b32_e32 v39, v96
	v_mov_b32_e32 v84, v96
	v_mov_b32_e32 v85, v96
	v_mov_b32_e32 v86, v96
	v_mov_b32_e32 v87, v96
	v_mov_b32_e32 v44, v96
	v_mov_b32_e32 v45, v96
	v_mov_b32_e32 v46, v96
	v_mov_b32_e32 v47, v96
	v_mov_b32_e32 v92, v96
	v_mov_b32_e32 v93, v96
	v_mov_b32_e32 v94, v96
	v_mov_b32_e32 v95, v96
	v_readfirstlane_b32 s32, v208
	s_cmp_ge_u32 s32, 256
	s_cbranch_scc0 .Lprio5_done
	s_setprio 1
.Lprio5_done:
.LBB0_574:
	ds_read_b128 v[128:131], v224
	ds_read_b128 v[132:135], v224 offset:1024
	ds_read_b128 v[136:139], v224 offset:2048
	ds_read_b128 v[140:143], v224 offset:3072
	ds_read_b128 v[144:147], v225
	ds_read_b128 v[148:151], v225 offset:1024
	ds_read_b128 v[152:155], v225 offset:2048
	ds_read_b128 v[156:159], v225 offset:3072
	s_add_u32 s0, s10, 0xfffc0080
	s_addc_u32 s1, s11, -1
	s_cmp_eq_u32 s21, 12
	s_cselect_b32 s15, s65, s1
	s_cselect_b32 s14, s64, s0
	s_cselect_b32 s13, s16, s20
	s_cselect_b32 s12, s17, s19
	v_lshl_add_u64 v[214:215], s[10:11], 0, v[186:187]
	s_add_i32 m0, s69, 0xc000
	ds_read_b128 v[160:163], v226
	ds_read_b128 v[164:167], v226 offset:1024
	ds_read_b128 v[168:171], v226 offset:2048
	ds_read_b128 v[172:175], v226 offset:3072
	ds_read_b128 v[196:199], v226 offset:4096
	ds_read_b128 v[200:203], v226 offset:5120
	ds_read_b128 v[204:207], v226 offset:6144
	ds_read_b128 v[210:213], v226 offset:7168
	global_load_lds_dwordx4 v[214:215], off
	v_lshl_add_u64 v[214:215], s[10:11], 0, v[188:189]
	s_add_i32 m0, s69, 0xe000
	s_nop 0
	global_load_lds_dwordx4 v[214:215], off
	s_waitcnt vmcnt(8)
	s_waitcnt lgkmcnt(0)
	s_barrier
; #define PG8_STAGE(bufoff, gbase, voff) do { _Pragma("unroll") for (int _i = 0; _i < 2; ++_i) \
;         __builtin_amdgcn_global_load_lds((const unsigned*)((const char*)(gbase) + (voff)[_i]), (PG8_LAS unsigned*)(lds + (bufoff) + ldsw + _i * 8192), 16, 0, 0); } while (0)
; #define PG8_LDA(dst, b, h) do { _Pragma("unroll") for (int m = 0; m < 4; ++m) _Pragma("unroll") for (int k = 0; k < 2; ++k) dst[m][k] = *(const PG8_LAS bf16x8*)(lds + PG8_SA(b, h) + aoff + m * 2048 + k * 1024); } while (0)
; #define PG8_MMA(ai, bj, At, Bt) do { __builtin_amdgcn_s_setprio(1); _Pragma("unroll") for (int m = 0; m < 4; ++m) _Pragma("unroll") for (int n = 0; n < 2; ++n) _Pragma("unroll") for (int k = 0; k < 2; ++k) \
;         acc[ai][bj][m][n] = __builtin_amdgcn_mfma_f32_16x16x32_bf16(Bt[n][k], At[m][k], acc[ai][bj][m][n], 0, 0, 0); __builtin_amdgcn_s_setprio(0); } while (0)
; #define PG8_WAIT_V(n) asm volatile("s_waitcnt vmcnt(" #n ")" ::: "memory")
; #define PG8_WAIT_L(n) asm volatile("s_waitcnt lgkmcnt(" #n ")" ::: "memory")
; #define PG8_BAR __builtin_amdgcn_s_barrier()
; #define PG8_SCHED __builtin_amdgcn_sched_barrier(0)
; template <class Epi, class Sched, bool ALIGN_EPI = false, bool SP2 = false>
; __device__ __forceinline__ void gemm_phase(PG8_LAS unsigned char* lds, const Gemm g, const Sched& S, const Epi& E) {
;     ...
;             PG8_WAIT_V(8); PG8_WAIT_L(0); PG8_BAR; PG8_MMA(0, 0, At, B0); PG8_MMA(0, 1, At, B1); PG8_BAR; PG8_SCHED;
;             PG8_LDA(At, 0, 1); PG8_STAGE(PG8_SB(0, 0), b2, voffB); PG8_STAGE(PG8_SB(0, 1), b2 + hstep, voffB); PG8_STAGE(PG8_SA(0, 0), a2, voffA);
;             PG8_WAIT_V(8); PG8_WAIT_L(0); PG8_BAR; PG8_MMA(1, 0, At, B0); PG8_MMA(1, 1, At, B1); PG8_BAR; PG8_SCHED;
	s_waitcnt lgkmcnt(0)
	v_mfma_f32_16x16x32_bf16 v[92:95], v[128:131], v[160:163], v[92:95]
	v_mfma_f32_16x16x32_bf16 v[44:47], v[136:139], v[160:163], v[44:47]
	v_mfma_f32_16x16x32_bf16 v[84:87], v[128:131], v[168:171], v[84:87]
	v_mfma_f32_16x16x32_bf16 v[36:39], v[136:139], v[168:171], v[36:39]
	v_mfma_f32_16x16x32_bf16 v[76:79], v[128:131], v[196:199], v[76:79]
	v_mfma_f32_16x16x32_bf16 v[28:31], v[136:139], v[196:199], v[28:31]
	v_mfma_f32_16x16x32_bf16 v[124:127], v[128:131], v[204:207], v[124:127]
	v_mfma_f32_16x16x32_bf16 v[120:123], v[136:139], v[204:207], v[120:123]
	v_mfma_f32_16x16x32_bf16 v[92:95], v[132:135], v[164:167], v[92:95]
	v_mfma_f32_16x16x32_bf16 v[44:47], v[140:143], v[164:167], v[44:47]
	v_mfma_f32_16x16x32_bf16 v[84:87], v[132:135], v[172:175], v[84:87]
	v_mfma_f32_16x16x32_bf16 v[36:39], v[140:143], v[172:175], v[36:39]
	v_mfma_f32_16x16x32_bf16 v[76:79], v[132:135], v[200:203], v[76:79]
	v_mfma_f32_16x16x32_bf16 v[28:31], v[140:143], v[200:203], v[28:31]
	v_mfma_f32_16x16x32_bf16 v[124:127], v[132:135], v[210:213], v[124:127]
	v_mfma_f32_16x16x32_bf16 v[120:123], v[140:143], v[210:213], v[120:123]
	v_mfma_f32_16x16x32_bf16 v[88:91], v[144:147], v[160:163], v[88:91]
	v_mfma_f32_16x16x32_bf16 v[40:43], v[152:155], v[160:163], v[40:43]
	v_mfma_f32_16x16x32_bf16 v[80:83], v[144:147], v[168:171], v[80:83]
	v_mfma_f32_16x16x32_bf16 v[32:35], v[152:155], v[168:171], v[32:35]
	v_mfma_f32_16x16x32_bf16 v[72:75], v[144:147], v[196:199], v[72:75]
	v_mfma_f32_16x16x32_bf16 v[24:27], v[152:155], v[196:199], v[24:27]
	v_mfma_f32_16x16x32_bf16 v[116:119], v[144:147], v[204:207], v[116:119]
	v_mfma_f32_16x16x32_bf16 v[112:115], v[152:155], v[204:207], v[112:115]
	v_mfma_f32_16x16x32_bf16 v[88:91], v[148:151], v[164:167], v[88:91]
	v_mfma_f32_16x16x32_bf16 v[40:43], v[156:159], v[164:167], v[40:43]
	v_mfma_f32_16x16x32_bf16 v[80:83], v[148:151], v[172:175], v[80:83]
	v_mfma_f32_16x16x32_bf16 v[32:35], v[156:159], v[172:175], v[32:35]
	v_mfma_f32_16x16x32_bf16 v[72:75], v[148:151], v[200:203], v[72:75]
	v_mfma_f32_16x16x32_bf16 v[24:27], v[156:159], v[200:203], v[24:27]
	v_mfma_f32_16x16x32_bf16 v[116:119], v[148:151], v[210:213], v[116:119]
	v_mfma_f32_16x16x32_bf16 v[112:115], v[156:159], v[210:213], v[112:115]
	s_barrier
	s_add_i32 s0, s97, s75
	v_lshl_add_u64 v[214:215], s[12:13], 0, v[178:179]
	s_mov_b32 m0, s0
	ds_read_b128 v[160:163], v226 offset:16384
	ds_read_b128 v[164:167], v226 offset:17408
	ds_read_b128 v[168:171], v226 offset:18432
	ds_read_b128 v[172:175], v226 offset:19456
	ds_read_b128 v[196:199], v226 offset:20480
	ds_read_b128 v[200:203], v226 offset:21504
	ds_read_b128 v[204:207], v226 offset:22528
	ds_read_b128 v[210:213], v226 offset:23552
	global_load_lds_dwordx4 v[214:215], off
	s_add_i32 m0, s0, 0x2000
	s_add_u32 s22, s12, 0x40000
	v_lshl_add_u64 v[216:217], s[12:13], 0, v[182:183]
	s_addc_u32 s23, s13, 0
	s_add_i32 s0, s72, s75
	global_load_lds_dwordx4 v[216:217], off
	v_lshl_add_u64 v[218:219], s[22:23], 0, v[178:179]
	s_mov_b32 m0, s0
	v_lshl_add_u64 v[220:221], s[14:15], 0, v[180:181]
	global_load_lds_dwordx4 v[218:219], off
	v_lshl_add_u64 v[218:219], s[22:23], 0, v[182:183]
	s_add_i32 m0, s0, 0x2000
	s_nop 0
	global_load_lds_dwordx4 v[218:219], off
	v_lshl_add_u64 v[218:219], s[14:15], 0, v[176:177]
	s_mov_b32 m0, s69
	s_nop 0
	global_load_lds_dwordx4 v[218:219], off
	s_mov_b32 m0, s76
	s_nop 0
	global_load_lds_dwordx4 v[220:221], off
	s_waitcnt vmcnt(8)
	s_waitcnt lgkmcnt(0)
	s_barrier
	s_waitcnt lgkmcnt(0)
	v_mfma_f32_16x16x32_bf16 v[68:71], v[128:131], v[160:163], v[68:71]
	v_mfma_f32_16x16x32_bf16 v[20:23], v[136:139], v[160:163], v[20:23]
	v_mfma_f32_16x16x32_bf16 v[60:63], v[128:131], v[168:171], v[60:63]
	v_mfma_f32_16x16x32_bf16 v[12:15], v[136:139], v[168:171], v[12:15]
	v_mfma_f32_16x16x32_bf16 v[52:55], v[128:131], v[196:199], v[52:55]
	v_mfma_f32_16x16x32_bf16 v[4:7], v[136:139], v[196:199], v[4:7]
	v_mfma_f32_16x16x32_bf16 v[108:111], v[128:131], v[204:207], v[108:111]
	v_mfma_f32_16x16x32_bf16 v[104:107], v[136:139], v[204:207], v[104:107]
	v_mfma_f32_16x16x32_bf16 v[68:71], v[132:135], v[164:167], v[68:71]
	v_mfma_f32_16x16x32_bf16 v[20:23], v[140:143], v[164:167], v[20:23]
	v_mfma_f32_16x16x32_bf16 v[60:63], v[132:135], v[172:175], v[60:63]
	v_mfma_f32_16x16x32_bf16 v[12:15], v[140:143], v[172:175], v[12:15]
	v_mfma_f32_16x16x32_bf16 v[52:55], v[132:135], v[200:203], v[52:55]
	v_mfma_f32_16x16x32_bf16 v[4:7], v[140:143], v[200:203], v[4:7]
	v_mfma_f32_16x16x32_bf16 v[108:111], v[132:135], v[210:213], v[108:111]
	v_mfma_f32_16x16x32_bf16 v[104:107], v[140:143], v[210:213], v[104:107]
	v_mfma_f32_16x16x32_bf16 v[64:67], v[144:147], v[160:163], v[64:67]
	v_mfma_f32_16x16x32_bf16 v[16:19], v[152:155], v[160:163], v[16:19]
	v_mfma_f32_16x16x32_bf16 v[56:59], v[144:147], v[168:171], v[56:59]
	v_mfma_f32_16x16x32_bf16 v[8:11], v[152:155], v[168:171], v[8:11]
	v_mfma_f32_16x16x32_bf16 v[48:51], v[144:147], v[196:199], v[48:51]
	v_mfma_f32_16x16x32_bf16 v[0:3], v[152:155], v[196:199], v[0:3]
	v_mfma_f32_16x16x32_bf16 v[100:103], v[144:147], v[204:207], v[100:103]
	v_mfma_f32_16x16x32_bf16 v[96:99], v[152:155], v[204:207], v[96:99]
	v_mfma_f32_16x16x32_bf16 v[64:67], v[148:151], v[164:167], v[64:67]
	v_mfma_f32_16x16x32_bf16 v[16:19], v[156:159], v[164:167], v[16:19]
	v_mfma_f32_16x16x32_bf16 v[56:59], v[148:151], v[172:175], v[56:59]
	v_mfma_f32_16x16x32_bf16 v[8:11], v[156:159], v[172:175], v[8:11]
	v_mfma_f32_16x16x32_bf16 v[48:51], v[148:151], v[200:203], v[48:51]
	v_mfma_f32_16x16x32_bf16 v[0:3], v[156:159], v[200:203], v[0:3]
	v_mfma_f32_16x16x32_bf16 v[100:103], v[148:151], v[210:213], v[100:103]
	v_mfma_f32_16x16x32_bf16 v[96:99], v[156:159], v[210:213], v[96:99]
	s_barrier
; #define PG8_STAGE(bufoff, gbase, voff) do { _Pragma("unroll") for (int _i = 0; _i < 2; ++_i) \
;         __builtin_amdgcn_global_load_lds((const unsigned*)((const char*)(gbase) + (voff)[_i]), (PG8_LAS unsigned*)(lds + (bufoff) + ldsw + _i * 8192), 16, 0, 0); } while (0)
; #define PG8_LDA(dst, b, h) do { _Pragma("unroll") for (int m = 0; m < 4; ++m) _Pragma("unroll") for (int k = 0; k < 2; ++k) dst[m][k] = *(const PG8_LAS bf16x8*)(lds + PG8_SA(b, h) + aoff + m * 2048 + k * 1024); } while (0)
; #define PG8_LDB(dst, b, h) do { _Pragma("unroll") for (int n = 0; n < 2; ++n) _Pragma("unroll") for (int k = 0; k < 2; ++k) dst[n][k] = *(const PG8_LAS bf16x8*)(lds + PG8_SB(b, h) + boff + n * 2048 + k * 1024); } while (0)
; #define PG8_MMA(ai, bj, At, Bt) do { __builtin_amdgcn_s_setprio(1); _Pragma("unroll") for (int m = 0; m < 4; ++m) _Pragma("unroll") for (int n = 0; n < 2; ++n) _Pragma("unroll") for (int k = 0; k < 2; ++k) \
;         acc[ai][bj][m][n] = __builtin_amdgcn_mfma_f32_16x16x32_bf16(Bt[n][k], At[m][k], acc[ai][bj][m][n], 0, 0, 0); __builtin_amdgcn_s_setprio(0); } while (0)
; #define PG8_WAIT_V(n) asm volatile("s_waitcnt vmcnt(" #n ")" ::: "memory")
; #define PG8_WAIT_L(n) asm volatile("s_waitcnt lgkmcnt(" #n ")" ::: "memory")
; #define PG8_BAR __builtin_amdgcn_s_barrier()
; #define PG8_SCHED __builtin_amdgcn_sched_barrier(0)
; template <class Epi, class Sched, bool ALIGN_EPI = false, bool SP2 = false>
; __device__ __forceinline__ void gemm_phase(PG8_LAS unsigned char* lds, const Gemm g, const Sched& S, const Epi& E) {
;     ...
;             PG8_LDB(B0, 1, 0); PG8_LDB(B1, 1, 1); PG8_SCHED; PG8_LDA(At, 1, 0); PG8_STAGE(PG8_SA(0, 1), a2 + hstep, voffA);
;             PG8_WAIT_V(8); PG8_WAIT_L(0); PG8_BAR; PG8_MMA(0, 0, At, B0); PG8_MMA(0, 1, At, B1); PG8_BAR; PG8_SCHED;
	s_add_i32 s0, 0, 0x18000
	s_add_i32 s1, 0, 0x1c000
	v_add_u32_e32 v140, s0, v223
	v_add_u32_e32 v156, s1, v223
	ds_read_b128 v[128:131], v140
	ds_read_b128 v[132:135], v140 offset:1024
	ds_read_b128 v[136:139], v140 offset:2048
	ds_read_b128 v[140:143], v140 offset:3072
	ds_read_b128 v[144:147], v156
	ds_read_b128 v[148:151], v156 offset:1024
	ds_read_b128 v[152:155], v156 offset:2048
	ds_read_b128 v[156:159], v156 offset:3072
	s_add_u32 s14, s14, 0x40000
	s_addc_u32 s15, s15, 0
	s_mov_b32 m0, s77
	v_lshl_add_u64 v[228:229], s[14:15], 0, v[176:177]
	ds_read_b128 v[160:163], v226 offset:32768
	ds_read_b128 v[164:167], v226 offset:33792
	ds_read_b128 v[168:171], v226 offset:34816
	ds_read_b128 v[172:175], v226 offset:35840
	ds_read_b128 v[196:199], v226 offset:36864
	ds_read_b128 v[200:203], v226 offset:37888
	ds_read_b128 v[204:207], v226 offset:38912
	ds_read_b128 v[210:213], v226 offset:39936
	global_load_lds_dwordx4 v[228:229], off
	v_lshl_add_u64 v[228:229], s[14:15], 0, v[180:181]
	s_mov_b32 m0, s78
	s_nop 0
	global_load_lds_dwordx4 v[228:229], off
	s_waitcnt vmcnt(8)
	s_waitcnt lgkmcnt(0)
	s_barrier
	s_waitcnt lgkmcnt(0)
	v_mfma_f32_16x16x32_bf16 v[92:95], v[128:131], v[160:163], v[92:95]
	v_mfma_f32_16x16x32_bf16 v[44:47], v[136:139], v[160:163], v[44:47]
	v_mfma_f32_16x16x32_bf16 v[84:87], v[128:131], v[168:171], v[84:87]
	v_mfma_f32_16x16x32_bf16 v[36:39], v[136:139], v[168:171], v[36:39]
	v_mfma_f32_16x16x32_bf16 v[76:79], v[128:131], v[196:199], v[76:79]
	v_mfma_f32_16x16x32_bf16 v[28:31], v[136:139], v[196:199], v[28:31]
	v_mfma_f32_16x16x32_bf16 v[124:127], v[128:131], v[204:207], v[124:127]
	v_mfma_f32_16x16x32_bf16 v[120:123], v[136:139], v[204:207], v[120:123]
	v_mfma_f32_16x16x32_bf16 v[92:95], v[132:135], v[164:167], v[92:95]
	v_mfma_f32_16x16x32_bf16 v[44:47], v[140:143], v[164:167], v[44:47]
	v_mfma_f32_16x16x32_bf16 v[84:87], v[132:135], v[172:175], v[84:87]
	v_mfma_f32_16x16x32_bf16 v[36:39], v[140:143], v[172:175], v[36:39]
	v_mfma_f32_16x16x32_bf16 v[76:79], v[132:135], v[200:203], v[76:79]
	v_mfma_f32_16x16x32_bf16 v[28:31], v[140:143], v[200:203], v[28:31]
	v_mfma_f32_16x16x32_bf16 v[124:127], v[132:135], v[210:213], v[124:127]
	v_mfma_f32_16x16x32_bf16 v[120:123], v[140:143], v[210:213], v[120:123]
	v_mfma_f32_16x16x32_bf16 v[88:91], v[144:147], v[160:163], v[88:91]
	v_mfma_f32_16x16x32_bf16 v[40:43], v[152:155], v[160:163], v[40:43]
	v_mfma_f32_16x16x32_bf16 v[80:83], v[144:147], v[168:171], v[80:83]
	v_mfma_f32_16x16x32_bf16 v[32:35], v[152:155], v[168:171], v[32:35]
	v_mfma_f32_16x16x32_bf16 v[72:75], v[144:147], v[196:199], v[72:75]
	v_mfma_f32_16x16x32_bf16 v[24:27], v[152:155], v[196:199], v[24:27]
	v_mfma_f32_16x16x32_bf16 v[116:119], v[144:147], v[204:207], v[116:119]
	v_mfma_f32_16x16x32_bf16 v[112:115], v[152:155], v[204:207], v[112:115]
	v_mfma_f32_16x16x32_bf16 v[88:91], v[148:151], v[164:167], v[88:91]
	v_mfma_f32_16x16x32_bf16 v[40:43], v[156:159], v[164:167], v[40:43]
	v_mfma_f32_16x16x32_bf16 v[80:83], v[148:151], v[172:175], v[80:83]
	v_mfma_f32_16x16x32_bf16 v[32:35], v[156:159], v[172:175], v[32:35]
	v_mfma_f32_16x16x32_bf16 v[72:75], v[148:151], v[200:203], v[72:75]
	v_mfma_f32_16x16x32_bf16 v[24:27], v[156:159], v[200:203], v[24:27]
	v_mfma_f32_16x16x32_bf16 v[116:119], v[148:151], v[210:213], v[116:119]
	v_mfma_f32_16x16x32_bf16 v[112:115], v[156:159], v[210:213], v[112:115]
	s_barrier
; #define PG8_STAGE(bufoff, gbase, voff) do { _Pragma("unroll") for (int _i = 0; _i < 2; ++_i) \
;         __builtin_amdgcn_global_load_lds((const unsigned*)((const char*)(gbase) + (voff)[_i]), (PG8_LAS unsigned*)(lds + (bufoff) + ldsw + _i * 8192), 16, 0, 0); } while (0)
; #define PG8_LDA(dst, b, h) do { _Pragma("unroll") for (int m = 0; m < 4; ++m) _Pragma("unroll") for (int k = 0; k < 2; ++k) dst[m][k] = *(const PG8_LAS bf16x8*)(lds + PG8_SA(b, h) + aoff + m * 2048 + k * 1024); } while (0)
; #define PG8_MMA(ai, bj, At, Bt) do { __builtin_amdgcn_s_setprio(1); _Pragma("unroll") for (int m = 0; m < 4; ++m) _Pragma("unroll") for (int n = 0; n < 2; ++n) _Pragma("unroll") for (int k = 0; k < 2; ++k) \
;         acc[ai][bj][m][n] = __builtin_amdgcn_mfma_f32_16x16x32_bf16(Bt[n][k], At[m][k], acc[ai][bj][m][n], 0, 0, 0); __builtin_amdgcn_s_setprio(0); } while (0)
; #define PG8_WAIT_V(n) asm volatile("s_waitcnt vmcnt(" #n ")" ::: "memory")
; #define PG8_WAIT_L(n) asm volatile("s_waitcnt lgkmcnt(" #n ")" ::: "memory")
; #define PG8_BAR __builtin_amdgcn_s_barrier()
; #define PG8_SCHED __builtin_amdgcn_sched_barrier(0)
; template <class Epi, class Sched, bool ALIGN_EPI = false, bool SP2 = false>
; __device__ __forceinline__ void gemm_phase(PG8_LAS unsigned char* lds, const Gemm g, const Sched& S, const Epi& E) {
;     ...
;         for (int t = 0; t < nt; t += 2) {
;     ...
;             PG8_LDA(At, 1, 1); PG8_STAGE(PG8_SB(1, 0), b3, voffB); PG8_STAGE(PG8_SB(1, 1), b3 + hstep, voffB); PG8_STAGE(PG8_SA(1, 0), a3, voffA);
;             PG8_WAIT_V(8); PG8_WAIT_L(0); PG8_BAR; PG8_MMA(1, 0, At, B0); PG8_MMA(1, 1, At, B1); PG8_BAR; PG8_SCHED;
	s_add_i32 s0, s0, s75
	v_lshl_add_u64 v[214:215], v[214:215], 0, s[40:41]
	s_mov_b32 m0, s0
	ds_read_b128 v[160:163], v226 offset:49152
	ds_read_b128 v[164:167], v226 offset:50176
	ds_read_b128 v[168:171], v226 offset:51200
	ds_read_b128 v[172:175], v226 offset:52224
	ds_read_b128 v[196:199], v226 offset:53248
	ds_read_b128 v[200:203], v226 offset:54272
	ds_read_b128 v[204:207], v226 offset:55296
	ds_read_b128 v[210:213], v226 offset:56320
	global_load_lds_dwordx4 v[214:215], off
	s_add_i32 m0, s0, 0x2000
	s_add_u32 s12, s12, 0x40080
	v_lshl_add_u64 v[214:215], v[216:217], 0, s[40:41]
	s_addc_u32 s13, s13, 0
	s_add_i32 s0, s1, s75
	global_load_lds_dwordx4 v[214:215], off
	v_lshl_add_u64 v[214:215], s[12:13], 0, v[178:179]
	s_mov_b32 m0, s0
	s_nop 0
	global_load_lds_dwordx4 v[214:215], off
	v_lshl_add_u64 v[214:215], s[12:13], 0, v[182:183]
	s_add_i32 m0, s0, 0x2000
	s_nop 0
	global_load_lds_dwordx4 v[214:215], off
	v_lshl_add_u64 v[214:215], v[218:219], 0, s[40:41]
	s_mov_b32 m0, s85
	s_nop 0
	global_load_lds_dwordx4 v[214:215], off
	v_lshl_add_u64 v[214:215], v[220:221], 0, s[40:41]
	s_mov_b32 m0, s86
	s_nop 0
	global_load_lds_dwordx4 v[214:215], off
	s_waitcnt vmcnt(8)
	s_waitcnt lgkmcnt(0)
	s_barrier
	s_waitcnt lgkmcnt(0)
	v_mfma_f32_16x16x32_bf16 v[68:71], v[128:131], v[160:163], v[68:71]
	v_mfma_f32_16x16x32_bf16 v[20:23], v[136:139], v[160:163], v[20:23]
	v_mfma_f32_16x16x32_bf16 v[60:63], v[128:131], v[168:171], v[60:63]
	v_mfma_f32_16x16x32_bf16 v[12:15], v[136:139], v[168:171], v[12:15]
	v_mfma_f32_16x16x32_bf16 v[52:55], v[128:131], v[196:199], v[52:55]
	v_mfma_f32_16x16x32_bf16 v[4:7], v[136:139], v[196:199], v[4:7]
	v_mfma_f32_16x16x32_bf16 v[108:111], v[128:131], v[204:207], v[108:111]
	v_mfma_f32_16x16x32_bf16 v[104:107], v[136:139], v[204:207], v[104:107]
	v_mfma_f32_16x16x32_bf16 v[68:71], v[132:135], v[164:167], v[68:71]
	v_mfma_f32_16x16x32_bf16 v[20:23], v[140:143], v[164:167], v[20:23]
	v_mfma_f32_16x16x32_bf16 v[60:63], v[132:135], v[172:175], v[60:63]
	v_mfma_f32_16x16x32_bf16 v[12:15], v[140:143], v[172:175], v[12:15]
	v_mfma_f32_16x16x32_bf16 v[52:55], v[132:135], v[200:203], v[52:55]
	v_mfma_f32_16x16x32_bf16 v[4:7], v[140:143], v[200:203], v[4:7]
	v_mfma_f32_16x16x32_bf16 v[108:111], v[132:135], v[210:213], v[108:111]
	v_mfma_f32_16x16x32_bf16 v[104:107], v[140:143], v[210:213], v[104:107]
	v_mfma_f32_16x16x32_bf16 v[64:67], v[144:147], v[160:163], v[64:67]
	v_mfma_f32_16x16x32_bf16 v[16:19], v[152:155], v[160:163], v[16:19]
	v_mfma_f32_16x16x32_bf16 v[56:59], v[144:147], v[168:171], v[56:59]
	v_mfma_f32_16x16x32_bf16 v[8:11], v[152:155], v[168:171], v[8:11]
	v_mfma_f32_16x16x32_bf16 v[48:51], v[144:147], v[196:199], v[48:51]
	v_mfma_f32_16x16x32_bf16 v[0:3], v[152:155], v[196:199], v[0:3]
	v_mfma_f32_16x16x32_bf16 v[100:103], v[144:147], v[204:207], v[100:103]
	v_mfma_f32_16x16x32_bf16 v[96:99], v[152:155], v[204:207], v[96:99]
	v_mfma_f32_16x16x32_bf16 v[64:67], v[148:151], v[164:167], v[64:67]
	v_mfma_f32_16x16x32_bf16 v[16:19], v[156:159], v[164:167], v[16:19]
	v_mfma_f32_16x16x32_bf16 v[56:59], v[148:151], v[172:175], v[56:59]
	v_mfma_f32_16x16x32_bf16 v[8:11], v[156:159], v[172:175], v[8:11]
	v_mfma_f32_16x16x32_bf16 v[48:51], v[148:151], v[200:203], v[48:51]
	v_mfma_f32_16x16x32_bf16 v[0:3], v[156:159], v[200:203], v[0:3]
	v_mfma_f32_16x16x32_bf16 v[100:103], v[148:151], v[210:213], v[100:103]
	v_mfma_f32_16x16x32_bf16 v[96:99], v[156:159], v[210:213], v[96:99]
	s_barrier
	s_add_i32 s21, s21, 2
	s_add_u32 s10, s10, 0x100
	s_addc_u32 s11, s11, 0
	s_add_u32 s19, s19, 0x100
	s_addc_u32 s20, s20, 0
	s_cmp_gt_u32 s21, 13
	s_cbranch_scc0 .LBB0_574
	s_setprio 0
	s_and_b64 vcc, exec, s[42:43]
	s_cbranch_vccnz .LBB0_579
	s_cmp_lg_u32 s18, 64
	s_mov_b64 s[10:11], -1
	s_cbranch_scc1 .LBB0_580
